# prologue de-serialisation: per-item NAT bias-table load issues both per-thread elements together with one wait instead of two serialized load/wait loops
# baseline (speedup 1.0000x reference)
.LBB0_491:
	s_cmp_eq_u32 s59, 3
	s_mov_b64 s[6:7], -1
	s_cbranch_scc0 .LBB0_550
	v_mov_b32_e32 v2, v234
	s_mov_b64 s[6:7], exec
	v_readlane_b32 s12, v253, 9
	v_readlane_b32 s30, v252, 63
	s_mulk_i32 s12, 0xe88
	s_mul_i32 s8, s10, 0x1d1
	v_readlane_b32 s31, v253, 0
	s_add_i32 s8, s12, s8
	v_readlane_b32 s14, v254, 22
	s_lshl_b64 s[12:13], s[8:9], 2
	v_mov_b32_e32 v4, v2
	s_add_u32 s12, s30, s12
	v_mov_b32_e32 v5, 0
	s_addc_u32 s13, s31, s13
	v_lshl_add_u64 v[4:5], v[4:5], 2, s[12:13]
	v_lshl_add_u32 v3, v2, 2, s14
	global_load_dword v6, v[4:5], off
	v_cmp_gt_u32_e32 vcc, 0xd1, v2
	s_and_saveexec_b64 s[14:15], vcc
	global_load_dword v7, v[4:5], off offset:1024
	s_or_b64 exec, exec, s[14:15]
	s_waitcnt vmcnt(0)
	ds_write_b32 v3, v6
	s_and_saveexec_b64 s[14:15], vcc
	ds_write_b32 v3, v7 offset:1024
	s_or_b64 exec, exec, s[14:15]
